# grid-barrier poll cap raised to the baseline's 2^18 spins (robustness only; no change on the normal path)
# baseline (speedup 1.0000x reference)
.Lxb2_poll:
	global_load_dword v2, v131, s[4:5] sc1
	s_add_i32 s7, s7, 1
	s_waitcnt vmcnt(0)
	v_cmp_lt_u32_e32 vcc, v2, v6
	s_nop 1
	s_cbranch_vccz .Lxb2_done
	s_sleep 1
	s_cmp_lt_u32 s7, 0x40001
	s_cbranch_scc1 .Lxb2_poll
